# P6 epilogue: residual x rows of the next 64-row pass loaded one pass ahead into dead registers
# baseline (speedup 1.0000x reference)
.LBB0_766:
	s_add_u32 s17, s10, 0x2000000
	s_addc_u32 s18, s11, 0
	s_add_u32 s15, s10, 0x1000000
	s_addc_u32 s16, s11, 0
	s_lshl_b32 s4, s47, 5
	s_barrier
	v_mbcnt_lo_u32_b32 v133, -1, 0
	v_mbcnt_hi_u32_b32 v133, -1, v133
	s_lshl_b32 s30, s33, 3
	v_and_or_b32 v132, v133, 15, s4
	s_lshl_b32 s4, s33, 4
	s_andn2_b32 s4, s4, 63
	s_lshl_b32 s6, s14, 8
	s_and_b32 s5, s30, 16
	s_add_i32 s6, s6, s4
	s_or_b32 s31, s6, s5
	s_movk_i32 s6, 0x410
	s_lshl_b32 s4, s8, 8
	v_mul_lo_u32 v132, v132, s6
	s_lshl_b32 s6, s49, 7
	s_ashr_i32 s5, s4, 31
	s_add_i32 s6, s6, 0
	s_and_b32 s19, s30, 8
	s_ashr_i32 s9, s8, 31
	v_lshlrev_b32_e32 v134, 1, v133
	v_add_u32_e32 v132, s6, v132
	s_lshl_b64 s[6:7], s[4:5], 2
	v_lshlrev_b32_e32 v130, 2, v133
	v_and_b32_e32 v134, 0xffffffe0, v134
	s_add_u32 s6, s12, s6
	v_ashrrev_i32_e32 v131, 31, v130
	v_add_u32_e32 v132, v132, v134
	s_addc_u32 s7, s13, s7
	ds_write_b128 v132, v[126:129]
	ds_write_b128 v132, v[122:125] offset:16
	ds_write_b128 v132, v[110:113] offset:512
	ds_write_b128 v132, v[106:109] offset:528
	ds_write_b128 v132, v[118:121] offset:16640
	ds_write_b128 v132, v[114:117] offset:16656
	ds_write_b128 v132, v[102:105] offset:17152
	ds_write_b128 v132, v[98:101] offset:17168
	v_lshl_add_u64 v[126:127], v[130:131], 2, s[6:7]
	s_or_b32 s6, s31, s19
	s_ashr_i32 s7, s6, 31
	s_lshl_b64 s[10:11], s[6:7], 12
	s_or_b32 s12, s19, 1
	v_lshl_add_u64 v[98:99], v[126:127], 0, s[10:11]
	s_or_b32 s10, s31, s12
	s_ashr_i32 s11, s10, 31
	s_lshl_b64 s[10:11], s[10:11], 12
	s_or_b32 s13, s19, 2
	v_lshl_add_u64 v[100:101], v[126:127], 0, s[10:11]
	s_or_b32 s10, s31, s13
	s_ashr_i32 s11, s10, 31
	s_lshl_b64 s[10:11], s[10:11], 12
	s_or_b32 s14, s19, 3
	s_waitcnt vmcnt(0) lgkmcnt(0)
	s_barrier
	global_load_dwordx4 v[134:137], v[98:99], off
	global_load_dwordx4 v[122:125], v[100:101], off
	v_lshl_add_u64 v[98:99], v[126:127], 0, s[10:11]
	s_or_b32 s10, s31, s14
	s_ashr_i32 s11, s10, 31
	s_lshl_b64 s[10:11], s[10:11], 12
	s_or_b32 s20, s19, 4
	v_lshl_add_u64 v[100:101], v[126:127], 0, s[10:11]
	s_or_b32 s10, s31, s20
	s_ashr_i32 s11, s10, 31
	s_lshl_b64 s[10:11], s[10:11], 12
	s_or_b32 s22, s19, 5
	global_load_dwordx4 v[118:121], v[98:99], off
	global_load_dwordx4 v[114:117], v[100:101], off
	v_lshl_add_u64 v[98:99], v[126:127], 0, s[10:11]
	s_or_b32 s10, s31, s22
	s_ashr_i32 s11, s10, 31
	s_lshl_b64 s[10:11], s[10:11], 12
	s_or_b32 s21, s19, 6
	v_lshl_add_u64 v[100:101], v[126:127], 0, s[10:11]
	s_or_b32 s10, s31, s21
	s_ashr_i32 s11, s10, 31
	s_lshl_b64 s[10:11], s[10:11], 12
	s_or_b32 s23, s19, 7
	global_load_dwordx4 v[110:113], v[98:99], off
	global_load_dwordx4 v[106:109], v[100:101], off
	v_lshl_add_u64 v[98:99], v[126:127], 0, s[10:11]
	s_or_b32 s10, s31, s23
	s_ashr_i32 s11, s10, 31
	s_lshl_b64 s[10:11], s[10:11], 12
	v_lshl_add_u64 v[100:101], v[126:127], 0, s[10:11]
	global_load_dwordx4 v[102:105], v[98:99], off
	s_nop 0
	global_load_dwordx4 v[98:101], v[100:101], off
	s_or_b32 s100, s31, 32
	s_or_b32 s98, s100, s19
	s_mov_b32 s99, 0
	s_lshl_b64 s[98:99], s[98:99], 12
	v_lshl_add_u64 v[142:143], v[126:127], 0, s[98:99]
	global_load_dwordx4 v[176:179], v[142:143], off
	s_or_b32 s98, s100, s12
	s_mov_b32 s99, 0
	s_lshl_b64 s[98:99], s[98:99], 12
	v_lshl_add_u64 v[142:143], v[126:127], 0, s[98:99]
	global_load_dwordx4 v[180:183], v[142:143], off
	s_or_b32 s98, s100, s13
	s_mov_b32 s99, 0
	s_lshl_b64 s[98:99], s[98:99], 12
	v_lshl_add_u64 v[142:143], v[126:127], 0, s[98:99]
	global_load_dwordx4 v[184:187], v[142:143], off
	s_or_b32 s98, s100, s14
	s_mov_b32 s99, 0
	s_lshl_b64 s[98:99], s[98:99], 12
	v_lshl_add_u64 v[142:143], v[126:127], 0, s[98:99]
	global_load_dwordx4 v[188:191], v[142:143], off
	s_or_b32 s98, s100, s20
	s_mov_b32 s99, 0
	s_lshl_b64 s[98:99], s[98:99], 12
	v_lshl_add_u64 v[142:143], v[126:127], 0, s[98:99]
	global_load_dwordx4 v[192:195], v[142:143], off
	s_or_b32 s98, s100, s22
	s_mov_b32 s99, 0
	s_lshl_b64 s[98:99], s[98:99], 12
	v_lshl_add_u64 v[142:143], v[126:127], 0, s[98:99]
	global_load_dwordx4 v[196:199], v[142:143], off
	s_or_b32 s98, s100, s21
	s_mov_b32 s99, 0
	s_lshl_b64 s[98:99], s[98:99], 12
	v_lshl_add_u64 v[142:143], v[126:127], 0, s[98:99]
	global_load_dwordx4 v[200:203], v[142:143], off
	s_or_b32 s98, s100, s23
	s_mov_b32 s99, 0
	s_lshl_b64 s[98:99], s[98:99], 12
	v_lshl_add_u64 v[142:143], v[126:127], 0, s[98:99]
	global_load_dwordx4 v[204:207], v[142:143], off
	v_lshl_add_u32 v128, v133, 4, 0
	s_mulk_i32 s33, 0x2080
	v_add_u32_e32 v129, s33, v128
	ds_read_b128 v[138:141], v129
	v_cmp_eq_u32_e32 vcc, 0, v133
	s_lshl_b64 s[10:11], s[6:7], 11
	s_add_u32 s10, s17, s10
	s_addc_u32 s11, s18, s11
	s_lshl_b64 s[4:5], s[4:5], 1
	s_add_u32 s10, s10, s4
	s_addc_u32 s11, s11, s5
	s_waitcnt vmcnt(15) lgkmcnt(0)
	v_pk_add_f32 v[134:135], v[134:135], v[138:139]
	v_pk_add_f32 v[136:137], v[136:137], v[140:141]
	v_mul_f32_e32 v133, v135, v135
	v_cvt_pk_bf16_f32 v138, v134, v135
	v_fmac_f32_e32 v133, v134, v134
	v_mul_f32_e32 v134, v137, v137
	v_fmac_f32_e32 v134, v136, v136
	v_add_f32_e32 v133, v133, v134
	v_cvt_pk_bf16_f32 v139, v136, v137
	v_lshl_add_u64 v[140:141], v[130:131], 1, s[10:11]
	v_add_f32_dpp v133, v133, v133 quad_perm:[1,0,3,2] row_mask:0xf bank_mask:0xf bound_ctrl:1
	global_store_dwordx2 v[140:141], v[138:139], off
	s_nop 0
	v_add_f32_dpp v133, v133, v133 quad_perm:[2,3,0,1] row_mask:0xf bank_mask:0xf bound_ctrl:1
	s_nop 1
	v_add_f32_dpp v133, v133, v133 row_half_mirror row_mask:0xf bank_mask:0xf bound_ctrl:1
	s_nop 1
	v_add_f32_dpp v133, v133, v133 row_mirror row_mask:0xf bank_mask:0xf bound_ctrl:1
	v_mov_b32_e32 v134, v133
	s_nop 1
	v_permlane16_swap_b32_e32 v133, v134
	v_add_f32_e32 v133, v133, v134
	v_mov_b32_e32 v134, v133
	s_nop 1
	v_permlane32_swap_b32_e32 v133, v134
	s_and_saveexec_b64 s[10:11], vcc
	s_cbranch_execz .LBB0_768
	s_lshl_b64 s[6:7], s[6:7], 4
	s_add_u32 s24, s15, s6
	s_addc_u32 s25, s16, s7
	s_lshl_b64 s[6:7], s[8:9], 2
	s_add_u32 s6, s24, s6
	s_addc_u32 s7, s25, s7
	v_mov_b32_e32 v135, 0
	v_add_f32_e32 v133, v133, v134
	global_store_dword v135, v133, s[6:7]
.LBB0_768:
	s_or_b64 exec, exec, s[10:11]
	s_or_b32 s6, s30, 1
	s_mul_i32 s7, s6, 0x410
	v_add_u32_e32 v128, s7, v128
	ds_read_b128 v[134:137], v128
	s_and_b32 s24, s6, 9
	s_or_b32 s6, s31, s24
	s_ashr_i32 s7, s6, 31
	s_lshl_b64 s[10:11], s[6:7], 11
	s_waitcnt vmcnt(15) lgkmcnt(0)
	v_pk_add_f32 v[122:123], v[122:123], v[134:135]
	v_pk_add_f32 v[124:125], v[124:125], v[136:137]
	v_cvt_pk_bf16_f32 v134, v122, v123
	v_mul_f32_e32 v123, v123, v123
	v_fmac_f32_e32 v123, v122, v122
	v_mul_f32_e32 v122, v125, v125
	v_fmac_f32_e32 v122, v124, v124
	v_add_f32_e32 v122, v123, v122
	s_add_u32 s10, s17, s10
	s_addc_u32 s11, s18, s11
	v_add_f32_dpp v122, v122, v122 quad_perm:[1,0,3,2] row_mask:0xf bank_mask:0xf bound_ctrl:1
	s_add_u32 s10, s10, s4
	s_addc_u32 s11, s11, s5
	v_add_f32_dpp v122, v122, v122 quad_perm:[2,3,0,1] row_mask:0xf bank_mask:0xf bound_ctrl:1
	v_cvt_pk_bf16_f32 v135, v124, v125
	v_lshl_add_u64 v[136:137], v[130:131], 1, s[10:11]
	v_add_f32_dpp v122, v122, v122 row_half_mirror row_mask:0xf bank_mask:0xf bound_ctrl:1
	global_store_dwordx2 v[136:137], v[134:135], off
	s_nop 0
	v_add_f32_dpp v122, v122, v122 row_mirror row_mask:0xf bank_mask:0xf bound_ctrl:1
	v_mov_b32_e32 v123, v122
	s_nop 1
	v_permlane16_swap_b32_e32 v122, v123
	v_add_f32_e32 v122, v122, v123
	v_mov_b32_e32 v123, v122
	s_nop 1
	v_permlane32_swap_b32_e32 v122, v123
	s_and_saveexec_b64 s[10:11], vcc
	s_cbranch_execz .LBB0_770
	s_lshl_b64 s[6:7], s[6:7], 4
	s_add_u32 s25, s15, s6
	s_addc_u32 s26, s16, s7
	s_lshl_b64 s[6:7], s[8:9], 2
	s_add_u32 s6, s25, s6
	s_addc_u32 s7, s26, s7
	v_mov_b32_e32 v124, 0
	v_add_f32_e32 v122, v122, v123
	global_store_dword v124, v122, s[6:7]
.LBB0_770:
	s_or_b64 exec, exec, s[10:11]
	ds_read_b128 v[122:125], v128 offset:1040
	s_or_b32 s6, s30, 2
	s_and_b32 s25, s6, 10
	s_or_b32 s6, s31, s25
	s_ashr_i32 s7, s6, 31
	s_waitcnt vmcnt(15) lgkmcnt(0)
	v_pk_add_f32 v[118:119], v[118:119], v[122:123]
	v_pk_add_f32 v[120:121], v[120:121], v[124:125]
	v_cvt_pk_bf16_f32 v122, v118, v119
	v_mul_f32_e32 v119, v119, v119
	v_fmac_f32_e32 v119, v118, v118
	v_mul_f32_e32 v118, v121, v121
	v_fmac_f32_e32 v118, v120, v120
	v_add_f32_e32 v118, v119, v118
	s_lshl_b64 s[10:11], s[6:7], 11
	s_add_u32 s10, s17, s10
	v_add_f32_dpp v118, v118, v118 quad_perm:[1,0,3,2] row_mask:0xf bank_mask:0xf bound_ctrl:1
	s_addc_u32 s11, s18, s11
	s_add_u32 s10, s10, s4
	v_add_f32_dpp v118, v118, v118 quad_perm:[2,3,0,1] row_mask:0xf bank_mask:0xf bound_ctrl:1
	s_addc_u32 s11, s11, s5
	v_cvt_pk_bf16_f32 v123, v120, v121
	v_add_f32_dpp v118, v118, v118 row_half_mirror row_mask:0xf bank_mask:0xf bound_ctrl:1
	v_lshl_add_u64 v[124:125], v[130:131], 1, s[10:11]
	global_store_dwordx2 v[124:125], v[122:123], off
	v_add_f32_dpp v118, v118, v118 row_mirror row_mask:0xf bank_mask:0xf bound_ctrl:1
	v_mov_b32_e32 v119, v118
	s_nop 1
	v_permlane16_swap_b32_e32 v118, v119
	v_add_f32_e32 v118, v118, v119
	v_mov_b32_e32 v119, v118
	s_nop 1
	v_permlane32_swap_b32_e32 v118, v119
	s_and_saveexec_b64 s[10:11], vcc
	s_cbranch_execz .LBB0_772
	s_lshl_b64 s[6:7], s[6:7], 4
	s_add_u32 s26, s15, s6
	s_addc_u32 s27, s16, s7
	s_lshl_b64 s[6:7], s[8:9], 2
	s_add_u32 s6, s26, s6
	s_addc_u32 s7, s27, s7
	v_mov_b32_e32 v120, 0
	v_add_f32_e32 v118, v118, v119
	global_store_dword v120, v118, s[6:7]
.LBB0_772:
	s_or_b64 exec, exec, s[10:11]
	ds_read_b128 v[118:121], v128 offset:2080
	s_or_b32 s6, s30, 3
	s_and_b32 s26, s6, 11
	s_or_b32 s6, s31, s26
	s_ashr_i32 s7, s6, 31
	s_waitcnt vmcnt(15) lgkmcnt(0)
	v_pk_add_f32 v[114:115], v[114:115], v[118:119]
	v_pk_add_f32 v[116:117], v[116:117], v[120:121]
	v_cvt_pk_bf16_f32 v118, v114, v115
	v_mul_f32_e32 v115, v115, v115
	v_fmac_f32_e32 v115, v114, v114
	v_mul_f32_e32 v114, v117, v117
	v_fmac_f32_e32 v114, v116, v116
	v_add_f32_e32 v114, v115, v114
	s_lshl_b64 s[10:11], s[6:7], 11
	s_add_u32 s10, s17, s10
	v_add_f32_dpp v114, v114, v114 quad_perm:[1,0,3,2] row_mask:0xf bank_mask:0xf bound_ctrl:1
	s_addc_u32 s11, s18, s11
	s_add_u32 s10, s10, s4
	v_add_f32_dpp v114, v114, v114 quad_perm:[2,3,0,1] row_mask:0xf bank_mask:0xf bound_ctrl:1
	s_addc_u32 s11, s11, s5
	v_cvt_pk_bf16_f32 v119, v116, v117
	v_add_f32_dpp v114, v114, v114 row_half_mirror row_mask:0xf bank_mask:0xf bound_ctrl:1
	v_lshl_add_u64 v[120:121], v[130:131], 1, s[10:11]
	global_store_dwordx2 v[120:121], v[118:119], off
	v_add_f32_dpp v114, v114, v114 row_mirror row_mask:0xf bank_mask:0xf bound_ctrl:1
	v_mov_b32_e32 v115, v114
	s_nop 1
	v_permlane16_swap_b32_e32 v114, v115
	v_add_f32_e32 v114, v114, v115
	v_mov_b32_e32 v115, v114
	s_nop 1
	v_permlane32_swap_b32_e32 v114, v115
	s_and_saveexec_b64 s[10:11], vcc
	s_cbranch_execz .LBB0_774
	s_lshl_b64 s[6:7], s[6:7], 4
	s_add_u32 s27, s15, s6
	s_addc_u32 s28, s16, s7
	s_lshl_b64 s[6:7], s[8:9], 2
	s_add_u32 s6, s27, s6
	s_addc_u32 s7, s28, s7
	v_mov_b32_e32 v116, 0
	v_add_f32_e32 v114, v114, v115
	global_store_dword v116, v114, s[6:7]
.LBB0_774:
	s_or_b64 exec, exec, s[10:11]
	ds_read_b128 v[114:117], v128 offset:3120
	s_or_b32 s6, s30, 4
	s_and_b32 s27, s6, 12
	s_or_b32 s6, s31, s27
	s_ashr_i32 s7, s6, 31
	s_waitcnt vmcnt(15) lgkmcnt(0)
	v_pk_add_f32 v[110:111], v[110:111], v[114:115]
	v_pk_add_f32 v[112:113], v[112:113], v[116:117]
	v_cvt_pk_bf16_f32 v114, v110, v111
	v_mul_f32_e32 v111, v111, v111
	v_fmac_f32_e32 v111, v110, v110
	v_mul_f32_e32 v110, v113, v113
	v_fmac_f32_e32 v110, v112, v112
	v_add_f32_e32 v110, v111, v110
	s_lshl_b64 s[10:11], s[6:7], 11
	s_add_u32 s10, s17, s10
	v_add_f32_dpp v110, v110, v110 quad_perm:[1,0,3,2] row_mask:0xf bank_mask:0xf bound_ctrl:1
	s_addc_u32 s11, s18, s11
	s_add_u32 s10, s10, s4
	v_add_f32_dpp v110, v110, v110 quad_perm:[2,3,0,1] row_mask:0xf bank_mask:0xf bound_ctrl:1
	s_addc_u32 s11, s11, s5
	v_cvt_pk_bf16_f32 v115, v112, v113
	v_add_f32_dpp v110, v110, v110 row_half_mirror row_mask:0xf bank_mask:0xf bound_ctrl:1
	v_lshl_add_u64 v[116:117], v[130:131], 1, s[10:11]
	global_store_dwordx2 v[116:117], v[114:115], off
	v_add_f32_dpp v110, v110, v110 row_mirror row_mask:0xf bank_mask:0xf bound_ctrl:1
	v_mov_b32_e32 v111, v110
	s_nop 1
	v_permlane16_swap_b32_e32 v110, v111
	v_add_f32_e32 v110, v110, v111
	v_mov_b32_e32 v111, v110
	s_nop 1
	v_permlane32_swap_b32_e32 v110, v111
	s_and_saveexec_b64 s[10:11], vcc
	s_cbranch_execz .LBB0_776
	s_lshl_b64 s[6:7], s[6:7], 4
	s_add_u32 s28, s15, s6
	s_addc_u32 s29, s16, s7
	s_lshl_b64 s[6:7], s[8:9], 2
	s_add_u32 s6, s28, s6
	s_addc_u32 s7, s29, s7
	v_mov_b32_e32 v112, 0
	v_add_f32_e32 v110, v110, v111
	global_store_dword v112, v110, s[6:7]
.LBB0_776:
	s_or_b64 exec, exec, s[10:11]
	ds_read_b128 v[110:113], v128 offset:4160
	s_or_b32 s6, s30, 5
	s_and_b32 s28, s6, 13
	s_or_b32 s6, s31, s28
	s_ashr_i32 s7, s6, 31
	s_waitcnt vmcnt(15) lgkmcnt(0)
	v_pk_add_f32 v[106:107], v[106:107], v[110:111]
	v_pk_add_f32 v[108:109], v[108:109], v[112:113]
	v_cvt_pk_bf16_f32 v110, v106, v107
	v_mul_f32_e32 v107, v107, v107
	v_fmac_f32_e32 v107, v106, v106
	v_mul_f32_e32 v106, v109, v109
	v_fmac_f32_e32 v106, v108, v108
	v_add_f32_e32 v106, v107, v106
	s_lshl_b64 s[10:11], s[6:7], 11
	s_add_u32 s10, s17, s10
	v_add_f32_dpp v106, v106, v106 quad_perm:[1,0,3,2] row_mask:0xf bank_mask:0xf bound_ctrl:1
	s_addc_u32 s11, s18, s11
	s_add_u32 s10, s10, s4
	v_add_f32_dpp v106, v106, v106 quad_perm:[2,3,0,1] row_mask:0xf bank_mask:0xf bound_ctrl:1
	s_addc_u32 s11, s11, s5
	v_cvt_pk_bf16_f32 v111, v108, v109
	v_add_f32_dpp v106, v106, v106 row_half_mirror row_mask:0xf bank_mask:0xf bound_ctrl:1
	v_lshl_add_u64 v[112:113], v[130:131], 1, s[10:11]
	global_store_dwordx2 v[112:113], v[110:111], off
	v_add_f32_dpp v106, v106, v106 row_mirror row_mask:0xf bank_mask:0xf bound_ctrl:1
	v_mov_b32_e32 v107, v106
	s_nop 1
	v_permlane16_swap_b32_e32 v106, v107
	v_add_f32_e32 v106, v106, v107
	v_mov_b32_e32 v107, v106
	s_nop 1
	v_permlane32_swap_b32_e32 v106, v107
	s_and_saveexec_b64 s[10:11], vcc
	s_cbranch_execz .LBB0_778
	s_lshl_b64 s[6:7], s[6:7], 4
	s_add_u32 s29, s15, s6
	s_addc_u32 s33, s16, s7
	s_lshl_b64 s[6:7], s[8:9], 2
	s_add_u32 s6, s29, s6
	s_addc_u32 s7, s33, s7
	v_mov_b32_e32 v108, 0
	v_add_f32_e32 v106, v106, v107
	global_store_dword v108, v106, s[6:7]
.LBB0_778:
	s_or_b64 exec, exec, s[10:11]
	ds_read_b128 v[106:109], v128 offset:5200
	s_or_b32 s6, s30, 6
	s_and_b32 s29, s6, 14
	s_or_b32 s6, s31, s29
	s_ashr_i32 s7, s6, 31
	s_waitcnt vmcnt(15) lgkmcnt(0)
	v_pk_add_f32 v[102:103], v[102:103], v[106:107]
	v_pk_add_f32 v[104:105], v[104:105], v[108:109]
	v_cvt_pk_bf16_f32 v106, v102, v103
	v_mul_f32_e32 v103, v103, v103
	v_fmac_f32_e32 v103, v102, v102
	v_mul_f32_e32 v102, v105, v105
	v_fmac_f32_e32 v102, v104, v104
	v_add_f32_e32 v102, v103, v102
	s_lshl_b64 s[10:11], s[6:7], 11
	s_add_u32 s10, s17, s10
	v_add_f32_dpp v102, v102, v102 quad_perm:[1,0,3,2] row_mask:0xf bank_mask:0xf bound_ctrl:1
	s_addc_u32 s11, s18, s11
	s_add_u32 s10, s10, s4
	v_add_f32_dpp v102, v102, v102 quad_perm:[2,3,0,1] row_mask:0xf bank_mask:0xf bound_ctrl:1
	s_addc_u32 s11, s11, s5
	v_cvt_pk_bf16_f32 v107, v104, v105
	v_add_f32_dpp v102, v102, v102 row_half_mirror row_mask:0xf bank_mask:0xf bound_ctrl:1
	v_lshl_add_u64 v[108:109], v[130:131], 1, s[10:11]
	global_store_dwordx2 v[108:109], v[106:107], off
	v_add_f32_dpp v102, v102, v102 row_mirror row_mask:0xf bank_mask:0xf bound_ctrl:1
	v_mov_b32_e32 v103, v102
	s_nop 1
	v_permlane16_swap_b32_e32 v102, v103
	v_add_f32_e32 v102, v102, v103
	v_mov_b32_e32 v103, v102
	s_nop 1
	v_permlane32_swap_b32_e32 v102, v103
	s_and_saveexec_b64 s[10:11], vcc
	s_cbranch_execz .LBB0_780
	s_lshl_b64 s[6:7], s[6:7], 4
	s_add_u32 s33, s15, s6
	s_addc_u32 s34, s16, s7
	s_lshl_b64 s[6:7], s[8:9], 2
	s_add_u32 s6, s33, s6
	s_addc_u32 s7, s34, s7
	v_mov_b32_e32 v104, 0
	v_add_f32_e32 v102, v102, v103
	global_store_dword v104, v102, s[6:7]
.LBB0_780:
	s_or_b64 exec, exec, s[10:11]
	ds_read_b128 v[102:105], v128 offset:6240
	s_or_b32 s6, s30, 7
	s_and_b32 s30, s6, 15
	s_or_b32 s6, s31, s30
	s_ashr_i32 s7, s6, 31
	s_waitcnt vmcnt(15) lgkmcnt(0)
	v_pk_add_f32 v[98:99], v[98:99], v[102:103]
	v_pk_add_f32 v[100:101], v[100:101], v[104:105]
	v_cvt_pk_bf16_f32 v102, v98, v99
	v_mul_f32_e32 v99, v99, v99
	v_fmac_f32_e32 v99, v98, v98
	v_mul_f32_e32 v98, v101, v101
	v_fmac_f32_e32 v98, v100, v100
	v_add_f32_e32 v98, v99, v98
	s_lshl_b64 s[10:11], s[6:7], 11
	s_add_u32 s10, s17, s10
	v_add_f32_dpp v98, v98, v98 quad_perm:[1,0,3,2] row_mask:0xf bank_mask:0xf bound_ctrl:1
	s_addc_u32 s11, s18, s11
	s_add_u32 s10, s10, s4
	v_add_f32_dpp v98, v98, v98 quad_perm:[2,3,0,1] row_mask:0xf bank_mask:0xf bound_ctrl:1
	s_addc_u32 s11, s11, s5
	v_cvt_pk_bf16_f32 v103, v100, v101
	v_add_f32_dpp v98, v98, v98 row_half_mirror row_mask:0xf bank_mask:0xf bound_ctrl:1
	v_lshl_add_u64 v[104:105], v[130:131], 1, s[10:11]
	global_store_dwordx2 v[104:105], v[102:103], off
	v_add_f32_dpp v98, v98, v98 row_mirror row_mask:0xf bank_mask:0xf bound_ctrl:1
	v_mov_b32_e32 v99, v98
	s_nop 1
	v_permlane16_swap_b32_e32 v98, v99
	v_add_f32_e32 v98, v98, v99
	v_mov_b32_e32 v99, v98
	s_nop 1
	v_permlane32_swap_b32_e32 v98, v99
	s_and_saveexec_b64 s[10:11], vcc
	s_cbranch_execz .LBB0_782
	s_lshl_b64 s[6:7], s[6:7], 4
	s_add_u32 s33, s15, s6
	s_addc_u32 s34, s16, s7
	s_lshl_b64 s[6:7], s[8:9], 2
	s_add_u32 s6, s33, s6
	s_addc_u32 s7, s34, s7
	v_mov_b32_e32 v100, 0
	v_add_f32_e32 v98, v98, v99
	global_store_dword v100, v98, s[6:7]
.LBB0_782:
	s_or_b64 exec, exec, s[10:11]
	s_or_b32 s33, s31, 32
	s_or_b32 s6, s33, s19
	s_ashr_i32 s7, s6, 31
	s_lshl_b64 s[10:11], s[6:7], 12
	s_barrier
	ds_write_b128 v132, v[94:97]
	ds_write_b128 v132, v[90:93] offset:16
	ds_write_b128 v132, v[78:81] offset:512
	ds_write_b128 v132, v[74:77] offset:528
	ds_write_b128 v132, v[86:89] offset:16640
	ds_write_b128 v132, v[82:85] offset:16656
	ds_write_b128 v132, v[70:73] offset:17152
	ds_write_b128 v132, v[66:69] offset:17168
	v_lshl_add_u64 v[66:67], v[126:127], 0, s[10:11]
	s_or_b32 s10, s33, s12
	s_ashr_i32 s11, s10, 31
	s_lshl_b64 s[10:11], s[10:11], 12
	v_lshl_add_u64 v[68:69], v[126:127], 0, s[10:11]
	s_or_b32 s10, s33, s13
	s_ashr_i32 s11, s10, 31
	s_lshl_b64 s[10:11], s[10:11], 12
	s_waitcnt lgkmcnt(0)
	s_barrier
	s_waitcnt vmcnt(8)
	v_mov_b32_e32 v94, v176
	v_mov_b32_e32 v95, v177
	v_mov_b32_e32 v96, v178
	v_mov_b32_e32 v97, v179
	v_mov_b32_e32 v90, v180
	v_mov_b32_e32 v91, v181
	v_mov_b32_e32 v92, v182
	v_mov_b32_e32 v93, v183
	v_mov_b32_e32 v86, v184
	v_mov_b32_e32 v87, v185
	v_mov_b32_e32 v88, v186
	v_mov_b32_e32 v89, v187
	v_mov_b32_e32 v82, v188
	v_mov_b32_e32 v83, v189
	v_mov_b32_e32 v84, v190
	v_mov_b32_e32 v85, v191
	v_mov_b32_e32 v78, v192
	v_mov_b32_e32 v79, v193
	v_mov_b32_e32 v80, v194
	v_mov_b32_e32 v81, v195
	v_mov_b32_e32 v74, v196
	v_mov_b32_e32 v75, v197
	v_mov_b32_e32 v76, v198
	v_mov_b32_e32 v77, v199
	v_mov_b32_e32 v70, v200
	v_mov_b32_e32 v71, v201
	v_mov_b32_e32 v72, v202
	v_mov_b32_e32 v73, v203
	v_mov_b32_e32 v66, v204
	v_mov_b32_e32 v67, v205
	v_mov_b32_e32 v68, v206
	v_mov_b32_e32 v69, v207
	s_add_i32 s100, s31, 0x80
	s_or_b32 s98, s100, s19
	s_mov_b32 s99, 0
	s_lshl_b64 s[98:99], s[98:99], 12
	v_lshl_add_u64 v[142:143], v[126:127], 0, s[98:99]
	global_load_dwordx4 v[144:147], v[142:143], off
	s_or_b32 s98, s100, s12
	s_mov_b32 s99, 0
	s_lshl_b64 s[98:99], s[98:99], 12
	v_lshl_add_u64 v[142:143], v[126:127], 0, s[98:99]
	global_load_dwordx4 v[148:151], v[142:143], off
	s_or_b32 s98, s100, s13
	s_mov_b32 s99, 0
	s_lshl_b64 s[98:99], s[98:99], 12
	v_lshl_add_u64 v[142:143], v[126:127], 0, s[98:99]
	global_load_dwordx4 v[152:155], v[142:143], off
	s_or_b32 s98, s100, s14
	s_mov_b32 s99, 0
	s_lshl_b64 s[98:99], s[98:99], 12
	v_lshl_add_u64 v[142:143], v[126:127], 0, s[98:99]
	global_load_dwordx4 v[156:159], v[142:143], off
	s_or_b32 s98, s100, s20
	s_mov_b32 s99, 0
	s_lshl_b64 s[98:99], s[98:99], 12
	v_lshl_add_u64 v[142:143], v[126:127], 0, s[98:99]
	global_load_dwordx4 v[160:163], v[142:143], off
	s_or_b32 s98, s100, s22
	s_mov_b32 s99, 0
	s_lshl_b64 s[98:99], s[98:99], 12
	v_lshl_add_u64 v[142:143], v[126:127], 0, s[98:99]
	global_load_dwordx4 v[164:167], v[142:143], off
	s_or_b32 s98, s100, s21
	s_mov_b32 s99, 0
	s_lshl_b64 s[98:99], s[98:99], 12
	v_lshl_add_u64 v[142:143], v[126:127], 0, s[98:99]
	global_load_dwordx4 v[168:171], v[142:143], off
	s_or_b32 s98, s100, s23
	s_mov_b32 s99, 0
	s_lshl_b64 s[98:99], s[98:99], 12
	v_lshl_add_u64 v[142:143], v[126:127], 0, s[98:99]
	global_load_dwordx4 v[172:175], v[142:143], off
	ds_read_b128 v[98:101], v129
	s_lshl_b64 s[10:11], s[6:7], 11
	s_add_u32 s10, s17, s10
	s_addc_u32 s11, s18, s11
	s_add_u32 s10, s10, s4
	s_addc_u32 s11, s11, s5
	v_lshl_add_u64 v[102:103], v[130:131], 1, s[10:11]
	s_waitcnt lgkmcnt(0)
	v_pk_add_f32 v[96:97], v[96:97], v[100:101]
	v_pk_add_f32 v[94:95], v[94:95], v[98:99]
	v_cvt_pk_bf16_f32 v99, v96, v97
	v_cvt_pk_bf16_f32 v98, v94, v95
	v_mul_f32_e32 v95, v95, v95
	v_mul_f32_e32 v97, v97, v97
	v_fmac_f32_e32 v95, v94, v94
	v_fmac_f32_e32 v97, v96, v96
	v_add_f32_e32 v94, v95, v97
	global_store_dwordx2 v[102:103], v[98:99], off
	s_nop 0
	v_add_f32_dpp v94, v94, v94 quad_perm:[1,0,3,2] row_mask:0xf bank_mask:0xf bound_ctrl:1
	s_nop 1
	v_add_f32_dpp v94, v94, v94 quad_perm:[2,3,0,1] row_mask:0xf bank_mask:0xf bound_ctrl:1
	s_nop 1
	v_add_f32_dpp v94, v94, v94 row_half_mirror row_mask:0xf bank_mask:0xf bound_ctrl:1
	s_nop 1
	v_add_f32_dpp v94, v94, v94 row_mirror row_mask:0xf bank_mask:0xf bound_ctrl:1
	v_mov_b32_e32 v95, v94
	s_nop 1
	v_permlane16_swap_b32_e32 v94, v95
	v_add_f32_e32 v94, v94, v95
	v_mov_b32_e32 v95, v94
	s_nop 1
	v_permlane32_swap_b32_e32 v94, v95
	s_and_saveexec_b64 s[10:11], vcc
	s_cbranch_execz .LBB0_784
	s_lshl_b64 s[6:7], s[6:7], 4
	s_add_u32 s34, s15, s6
	s_addc_u32 s35, s16, s7
	s_lshl_b64 s[6:7], s[8:9], 2
	s_add_u32 s6, s34, s6
	s_addc_u32 s7, s35, s7
	v_mov_b32_e32 v96, 0
	v_add_f32_e32 v94, v94, v95
	global_store_dword v96, v94, s[6:7]
.LBB0_784:
	s_or_b64 exec, exec, s[10:11]
	ds_read_b128 v[94:97], v128
	s_or_b32 s6, s33, s24
	s_ashr_i32 s7, s6, 31
	s_lshl_b64 s[10:11], s[6:7], 11
	s_add_u32 s10, s17, s10
	s_waitcnt lgkmcnt(0)
	v_pk_add_f32 v[90:91], v[90:91], v[94:95]
	v_pk_add_f32 v[92:93], v[92:93], v[96:97]
	v_cvt_pk_bf16_f32 v94, v90, v91
	v_mul_f32_e32 v91, v91, v91
	v_fmac_f32_e32 v91, v90, v90
	v_mul_f32_e32 v90, v93, v93
	v_fmac_f32_e32 v90, v92, v92
	v_add_f32_e32 v90, v91, v90
	s_addc_u32 s11, s18, s11
	s_add_u32 s10, s10, s4
	v_add_f32_dpp v90, v90, v90 quad_perm:[1,0,3,2] row_mask:0xf bank_mask:0xf bound_ctrl:1
	s_addc_u32 s11, s11, s5
	v_cvt_pk_bf16_f32 v95, v92, v93
	v_add_f32_dpp v90, v90, v90 quad_perm:[2,3,0,1] row_mask:0xf bank_mask:0xf bound_ctrl:1
	v_lshl_add_u64 v[96:97], v[130:131], 1, s[10:11]
	global_store_dwordx2 v[96:97], v[94:95], off
	v_add_f32_dpp v90, v90, v90 row_half_mirror row_mask:0xf bank_mask:0xf bound_ctrl:1
	s_nop 1
	v_add_f32_dpp v90, v90, v90 row_mirror row_mask:0xf bank_mask:0xf bound_ctrl:1
	v_mov_b32_e32 v91, v90
	s_nop 1
	v_permlane16_swap_b32_e32 v90, v91
	v_add_f32_e32 v90, v90, v91
	v_mov_b32_e32 v91, v90
	s_nop 1
	v_permlane32_swap_b32_e32 v90, v91
	s_and_saveexec_b64 s[10:11], vcc
	s_cbranch_execz .LBB0_786
	s_lshl_b64 s[6:7], s[6:7], 4
	s_add_u32 s34, s15, s6
	s_addc_u32 s35, s16, s7
	s_lshl_b64 s[6:7], s[8:9], 2
	s_add_u32 s6, s34, s6
	s_addc_u32 s7, s35, s7
	v_mov_b32_e32 v92, 0
	v_add_f32_e32 v90, v90, v91
	global_store_dword v92, v90, s[6:7]
.LBB0_786:
	s_or_b64 exec, exec, s[10:11]
	ds_read_b128 v[90:93], v128 offset:1040
	s_or_b32 s6, s33, s25
	s_ashr_i32 s7, s6, 31
	s_lshl_b64 s[10:11], s[6:7], 11
	s_add_u32 s10, s17, s10
	s_waitcnt lgkmcnt(0)
	v_pk_add_f32 v[86:87], v[86:87], v[90:91]
	v_pk_add_f32 v[88:89], v[88:89], v[92:93]
	v_cvt_pk_bf16_f32 v90, v86, v87
	v_mul_f32_e32 v87, v87, v87
	v_fmac_f32_e32 v87, v86, v86
	v_mul_f32_e32 v86, v89, v89
	v_fmac_f32_e32 v86, v88, v88
	v_add_f32_e32 v86, v87, v86
	s_addc_u32 s11, s18, s11
	s_add_u32 s10, s10, s4
	v_add_f32_dpp v86, v86, v86 quad_perm:[1,0,3,2] row_mask:0xf bank_mask:0xf bound_ctrl:1
	s_addc_u32 s11, s11, s5
	v_cvt_pk_bf16_f32 v91, v88, v89
	v_add_f32_dpp v86, v86, v86 quad_perm:[2,3,0,1] row_mask:0xf bank_mask:0xf bound_ctrl:1
	v_lshl_add_u64 v[92:93], v[130:131], 1, s[10:11]
	global_store_dwordx2 v[92:93], v[90:91], off
	v_add_f32_dpp v86, v86, v86 row_half_mirror row_mask:0xf bank_mask:0xf bound_ctrl:1
	s_nop 1
	v_add_f32_dpp v86, v86, v86 row_mirror row_mask:0xf bank_mask:0xf bound_ctrl:1
	v_mov_b32_e32 v87, v86
	s_nop 1
	v_permlane16_swap_b32_e32 v86, v87
	v_add_f32_e32 v86, v86, v87
	v_mov_b32_e32 v87, v86
	s_nop 1
	v_permlane32_swap_b32_e32 v86, v87
	s_and_saveexec_b64 s[10:11], vcc
	s_cbranch_execz .LBB0_788
	s_lshl_b64 s[6:7], s[6:7], 4
	s_add_u32 s34, s15, s6
	s_addc_u32 s35, s16, s7
	s_lshl_b64 s[6:7], s[8:9], 2
	s_add_u32 s6, s34, s6
	s_addc_u32 s7, s35, s7
	v_mov_b32_e32 v88, 0
	v_add_f32_e32 v86, v86, v87
	global_store_dword v88, v86, s[6:7]
.LBB0_788:
	s_or_b64 exec, exec, s[10:11]
	ds_read_b128 v[86:89], v128 offset:2080
	s_or_b32 s6, s33, s26
	s_ashr_i32 s7, s6, 31
	s_lshl_b64 s[10:11], s[6:7], 11
	s_add_u32 s10, s17, s10
	s_waitcnt lgkmcnt(0)
	v_pk_add_f32 v[82:83], v[82:83], v[86:87]
	v_pk_add_f32 v[84:85], v[84:85], v[88:89]
	v_cvt_pk_bf16_f32 v86, v82, v83
	v_mul_f32_e32 v83, v83, v83
	v_fmac_f32_e32 v83, v82, v82
	v_mul_f32_e32 v82, v85, v85
	v_fmac_f32_e32 v82, v84, v84
	v_add_f32_e32 v82, v83, v82
	s_addc_u32 s11, s18, s11
	s_add_u32 s10, s10, s4
	v_add_f32_dpp v82, v82, v82 quad_perm:[1,0,3,2] row_mask:0xf bank_mask:0xf bound_ctrl:1
	s_addc_u32 s11, s11, s5
	v_cvt_pk_bf16_f32 v87, v84, v85
	v_add_f32_dpp v82, v82, v82 quad_perm:[2,3,0,1] row_mask:0xf bank_mask:0xf bound_ctrl:1
	v_lshl_add_u64 v[88:89], v[130:131], 1, s[10:11]
	global_store_dwordx2 v[88:89], v[86:87], off
	v_add_f32_dpp v82, v82, v82 row_half_mirror row_mask:0xf bank_mask:0xf bound_ctrl:1
	s_nop 1
	v_add_f32_dpp v82, v82, v82 row_mirror row_mask:0xf bank_mask:0xf bound_ctrl:1
	v_mov_b32_e32 v83, v82
	s_nop 1
	v_permlane16_swap_b32_e32 v82, v83
	v_add_f32_e32 v82, v82, v83
	v_mov_b32_e32 v83, v82
	s_nop 1
	v_permlane32_swap_b32_e32 v82, v83
	s_and_saveexec_b64 s[10:11], vcc
	s_cbranch_execz .LBB0_790
	s_lshl_b64 s[6:7], s[6:7], 4
	s_add_u32 s34, s15, s6
	s_addc_u32 s35, s16, s7
	s_lshl_b64 s[6:7], s[8:9], 2
	s_add_u32 s6, s34, s6
	s_addc_u32 s7, s35, s7
	v_mov_b32_e32 v84, 0
	v_add_f32_e32 v82, v82, v83
	global_store_dword v84, v82, s[6:7]
.LBB0_790:
	s_or_b64 exec, exec, s[10:11]
	ds_read_b128 v[82:85], v128 offset:3120
	s_or_b32 s6, s33, s27
	s_ashr_i32 s7, s6, 31
	s_lshl_b64 s[10:11], s[6:7], 11
	s_add_u32 s10, s17, s10
	s_waitcnt lgkmcnt(0)
	v_pk_add_f32 v[78:79], v[78:79], v[82:83]
	v_pk_add_f32 v[80:81], v[80:81], v[84:85]
	v_cvt_pk_bf16_f32 v82, v78, v79
	v_mul_f32_e32 v79, v79, v79
	v_fmac_f32_e32 v79, v78, v78
	v_mul_f32_e32 v78, v81, v81
	v_fmac_f32_e32 v78, v80, v80
	v_add_f32_e32 v78, v79, v78
	s_addc_u32 s11, s18, s11
	s_add_u32 s10, s10, s4
	v_add_f32_dpp v78, v78, v78 quad_perm:[1,0,3,2] row_mask:0xf bank_mask:0xf bound_ctrl:1
	s_addc_u32 s11, s11, s5
	v_cvt_pk_bf16_f32 v83, v80, v81
	v_add_f32_dpp v78, v78, v78 quad_perm:[2,3,0,1] row_mask:0xf bank_mask:0xf bound_ctrl:1
	v_lshl_add_u64 v[84:85], v[130:131], 1, s[10:11]
	global_store_dwordx2 v[84:85], v[82:83], off
	v_add_f32_dpp v78, v78, v78 row_half_mirror row_mask:0xf bank_mask:0xf bound_ctrl:1
	s_nop 1
	v_add_f32_dpp v78, v78, v78 row_mirror row_mask:0xf bank_mask:0xf bound_ctrl:1
	v_mov_b32_e32 v79, v78
	s_nop 1
	v_permlane16_swap_b32_e32 v78, v79
	v_add_f32_e32 v78, v78, v79
	v_mov_b32_e32 v79, v78
	s_nop 1
	v_permlane32_swap_b32_e32 v78, v79
	s_and_saveexec_b64 s[10:11], vcc
	s_cbranch_execz .LBB0_792
	s_lshl_b64 s[6:7], s[6:7], 4
	s_add_u32 s34, s15, s6
	s_addc_u32 s35, s16, s7
	s_lshl_b64 s[6:7], s[8:9], 2
	s_add_u32 s6, s34, s6
	s_addc_u32 s7, s35, s7
	v_mov_b32_e32 v80, 0
	v_add_f32_e32 v78, v78, v79
	global_store_dword v80, v78, s[6:7]
.LBB0_792:
	s_or_b64 exec, exec, s[10:11]
	ds_read_b128 v[78:81], v128 offset:4160
	s_or_b32 s6, s33, s28
	s_ashr_i32 s7, s6, 31
	s_lshl_b64 s[10:11], s[6:7], 11
	s_add_u32 s10, s17, s10
	s_waitcnt lgkmcnt(0)
	v_pk_add_f32 v[74:75], v[74:75], v[78:79]
	v_pk_add_f32 v[76:77], v[76:77], v[80:81]
	v_cvt_pk_bf16_f32 v78, v74, v75
	v_mul_f32_e32 v75, v75, v75
	v_fmac_f32_e32 v75, v74, v74
	v_mul_f32_e32 v74, v77, v77
	v_fmac_f32_e32 v74, v76, v76
	v_add_f32_e32 v74, v75, v74
	s_addc_u32 s11, s18, s11
	s_add_u32 s10, s10, s4
	v_add_f32_dpp v74, v74, v74 quad_perm:[1,0,3,2] row_mask:0xf bank_mask:0xf bound_ctrl:1
	s_addc_u32 s11, s11, s5
	v_cvt_pk_bf16_f32 v79, v76, v77
	v_add_f32_dpp v74, v74, v74 quad_perm:[2,3,0,1] row_mask:0xf bank_mask:0xf bound_ctrl:1
	v_lshl_add_u64 v[80:81], v[130:131], 1, s[10:11]
	global_store_dwordx2 v[80:81], v[78:79], off
	v_add_f32_dpp v74, v74, v74 row_half_mirror row_mask:0xf bank_mask:0xf bound_ctrl:1
	s_nop 1
	v_add_f32_dpp v74, v74, v74 row_mirror row_mask:0xf bank_mask:0xf bound_ctrl:1
	v_mov_b32_e32 v75, v74
	s_nop 1
	v_permlane16_swap_b32_e32 v74, v75
	v_add_f32_e32 v74, v74, v75
	v_mov_b32_e32 v75, v74
	s_nop 1
	v_permlane32_swap_b32_e32 v74, v75
	s_and_saveexec_b64 s[10:11], vcc
	s_cbranch_execz .LBB0_794
	s_lshl_b64 s[6:7], s[6:7], 4
	s_add_u32 s34, s15, s6
	s_addc_u32 s35, s16, s7
	s_lshl_b64 s[6:7], s[8:9], 2
	s_add_u32 s6, s34, s6
	s_addc_u32 s7, s35, s7
	v_mov_b32_e32 v76, 0
	v_add_f32_e32 v74, v74, v75
	global_store_dword v76, v74, s[6:7]
.LBB0_794:
	s_or_b64 exec, exec, s[10:11]
	ds_read_b128 v[74:77], v128 offset:5200
	s_or_b32 s6, s33, s29
	s_ashr_i32 s7, s6, 31
	s_lshl_b64 s[10:11], s[6:7], 11
	s_add_u32 s10, s17, s10
	s_waitcnt lgkmcnt(0)
	v_pk_add_f32 v[70:71], v[70:71], v[74:75]
	v_pk_add_f32 v[72:73], v[72:73], v[76:77]
	v_cvt_pk_bf16_f32 v74, v70, v71
	v_mul_f32_e32 v71, v71, v71
	v_fmac_f32_e32 v71, v70, v70
	v_mul_f32_e32 v70, v73, v73
	v_fmac_f32_e32 v70, v72, v72
	v_add_f32_e32 v70, v71, v70
	s_addc_u32 s11, s18, s11
	s_add_u32 s10, s10, s4
	v_add_f32_dpp v70, v70, v70 quad_perm:[1,0,3,2] row_mask:0xf bank_mask:0xf bound_ctrl:1
	s_addc_u32 s11, s11, s5
	v_cvt_pk_bf16_f32 v75, v72, v73
	v_add_f32_dpp v70, v70, v70 quad_perm:[2,3,0,1] row_mask:0xf bank_mask:0xf bound_ctrl:1
	v_lshl_add_u64 v[76:77], v[130:131], 1, s[10:11]
	global_store_dwordx2 v[76:77], v[74:75], off
	v_add_f32_dpp v70, v70, v70 row_half_mirror row_mask:0xf bank_mask:0xf bound_ctrl:1
	s_nop 1
	v_add_f32_dpp v70, v70, v70 row_mirror row_mask:0xf bank_mask:0xf bound_ctrl:1
	v_mov_b32_e32 v71, v70
	s_nop 1
	v_permlane16_swap_b32_e32 v70, v71
	v_add_f32_e32 v70, v70, v71
	v_mov_b32_e32 v71, v70
	s_nop 1
	v_permlane32_swap_b32_e32 v70, v71
	s_and_saveexec_b64 s[10:11], vcc
	s_cbranch_execz .LBB0_796
	s_lshl_b64 s[6:7], s[6:7], 4
	s_add_u32 s34, s15, s6
	s_addc_u32 s35, s16, s7
	s_lshl_b64 s[6:7], s[8:9], 2
	s_add_u32 s6, s34, s6
	s_addc_u32 s7, s35, s7
	v_mov_b32_e32 v72, 0
	v_add_f32_e32 v70, v70, v71
	global_store_dword v72, v70, s[6:7]
.LBB0_796:
	s_or_b64 exec, exec, s[10:11]
	ds_read_b128 v[70:73], v128 offset:6240
	s_or_b32 s6, s33, s30
	s_ashr_i32 s7, s6, 31
	s_lshl_b64 s[10:11], s[6:7], 11
	s_add_u32 s10, s17, s10
	s_waitcnt lgkmcnt(0)
	v_pk_add_f32 v[66:67], v[66:67], v[70:71]
	v_pk_add_f32 v[68:69], v[68:69], v[72:73]
	v_cvt_pk_bf16_f32 v70, v66, v67
	v_mul_f32_e32 v67, v67, v67
	v_fmac_f32_e32 v67, v66, v66
	v_mul_f32_e32 v66, v69, v69
	v_fmac_f32_e32 v66, v68, v68
	v_add_f32_e32 v66, v67, v66
	s_addc_u32 s11, s18, s11
	s_add_u32 s10, s10, s4
	v_add_f32_dpp v66, v66, v66 quad_perm:[1,0,3,2] row_mask:0xf bank_mask:0xf bound_ctrl:1
	s_addc_u32 s11, s11, s5
	v_cvt_pk_bf16_f32 v71, v68, v69
	v_add_f32_dpp v66, v66, v66 quad_perm:[2,3,0,1] row_mask:0xf bank_mask:0xf bound_ctrl:1
	v_lshl_add_u64 v[72:73], v[130:131], 1, s[10:11]
	global_store_dwordx2 v[72:73], v[70:71], off
	v_add_f32_dpp v66, v66, v66 row_half_mirror row_mask:0xf bank_mask:0xf bound_ctrl:1
	s_nop 1
	v_add_f32_dpp v66, v66, v66 row_mirror row_mask:0xf bank_mask:0xf bound_ctrl:1
	v_mov_b32_e32 v67, v66
	s_nop 1
	v_permlane16_swap_b32_e32 v66, v67
	v_add_f32_e32 v66, v66, v67
	v_mov_b32_e32 v67, v66
	s_nop 1
	v_permlane32_swap_b32_e32 v66, v67
	s_and_saveexec_b64 s[10:11], vcc
	s_cbranch_execz .LBB0_798
	s_lshl_b64 s[6:7], s[6:7], 4
	s_add_u32 s33, s15, s6
	s_addc_u32 s34, s16, s7
	s_lshl_b64 s[6:7], s[8:9], 2
	s_add_u32 s6, s33, s6
	s_addc_u32 s7, s34, s7
	v_mov_b32_e32 v68, 0
	v_add_f32_e32 v66, v66, v67
	global_store_dword v68, v66, s[6:7]
.LBB0_798:
	s_or_b64 exec, exec, s[10:11]
	s_addk_i32 s31, 0x80
	s_or_b32 s6, s31, s19
	s_ashr_i32 s7, s6, 31
	s_lshl_b64 s[10:11], s[6:7], 12
	s_barrier
	ds_write_b128 v132, v[62:65]
	ds_write_b128 v132, v[58:61] offset:16
	ds_write_b128 v132, v[46:49] offset:512
	ds_write_b128 v132, v[42:45] offset:528
	ds_write_b128 v132, v[54:57] offset:16640
	ds_write_b128 v132, v[50:53] offset:16656
	ds_write_b128 v132, v[38:41] offset:17152
	ds_write_b128 v132, v[34:37] offset:17168
	v_lshl_add_u64 v[34:35], v[126:127], 0, s[10:11]
	s_or_b32 s10, s31, s12
	s_ashr_i32 s11, s10, 31
	s_lshl_b64 s[10:11], s[10:11], 12
	v_lshl_add_u64 v[36:37], v[126:127], 0, s[10:11]
	s_or_b32 s10, s31, s13
	s_ashr_i32 s11, s10, 31
	s_lshl_b64 s[10:11], s[10:11], 12
	s_waitcnt lgkmcnt(0)
	s_barrier
	s_waitcnt vmcnt(8)
	v_mov_b32_e32 v62, v144
	v_mov_b32_e32 v63, v145
	v_mov_b32_e32 v64, v146
	v_mov_b32_e32 v65, v147
	v_mov_b32_e32 v58, v148
	v_mov_b32_e32 v59, v149
	v_mov_b32_e32 v60, v150
	v_mov_b32_e32 v61, v151
	v_mov_b32_e32 v54, v152
	v_mov_b32_e32 v55, v153
	v_mov_b32_e32 v56, v154
	v_mov_b32_e32 v57, v155
	v_mov_b32_e32 v50, v156
	v_mov_b32_e32 v51, v157
	v_mov_b32_e32 v52, v158
	v_mov_b32_e32 v53, v159
	v_mov_b32_e32 v46, v160
	v_mov_b32_e32 v47, v161
	v_mov_b32_e32 v48, v162
	v_mov_b32_e32 v49, v163
	v_mov_b32_e32 v42, v164
	v_mov_b32_e32 v43, v165
	v_mov_b32_e32 v44, v166
	v_mov_b32_e32 v45, v167
	v_mov_b32_e32 v38, v168
	v_mov_b32_e32 v39, v169
	v_mov_b32_e32 v40, v170
	v_mov_b32_e32 v41, v171
	v_mov_b32_e32 v34, v172
	v_mov_b32_e32 v35, v173
	v_mov_b32_e32 v36, v174
	v_mov_b32_e32 v37, v175
	s_or_b32 s100, s31, 32
	s_or_b32 s98, s100, s19
	s_mov_b32 s99, 0
	s_lshl_b64 s[98:99], s[98:99], 12
	v_lshl_add_u64 v[142:143], v[126:127], 0, s[98:99]
	global_load_dwordx4 v[176:179], v[142:143], off
	s_or_b32 s98, s100, s12
	s_mov_b32 s99, 0
	s_lshl_b64 s[98:99], s[98:99], 12
	v_lshl_add_u64 v[142:143], v[126:127], 0, s[98:99]
	global_load_dwordx4 v[180:183], v[142:143], off
	s_or_b32 s98, s100, s13
	s_mov_b32 s99, 0
	s_lshl_b64 s[98:99], s[98:99], 12
	v_lshl_add_u64 v[142:143], v[126:127], 0, s[98:99]
	global_load_dwordx4 v[184:187], v[142:143], off
	s_or_b32 s98, s100, s14
	s_mov_b32 s99, 0
	s_lshl_b64 s[98:99], s[98:99], 12
	v_lshl_add_u64 v[142:143], v[126:127], 0, s[98:99]
	global_load_dwordx4 v[188:191], v[142:143], off
	s_or_b32 s98, s100, s20
	s_mov_b32 s99, 0
	s_lshl_b64 s[98:99], s[98:99], 12
	v_lshl_add_u64 v[142:143], v[126:127], 0, s[98:99]
	global_load_dwordx4 v[192:195], v[142:143], off
	s_or_b32 s98, s100, s22
	s_mov_b32 s99, 0
	s_lshl_b64 s[98:99], s[98:99], 12
	v_lshl_add_u64 v[142:143], v[126:127], 0, s[98:99]
	global_load_dwordx4 v[196:199], v[142:143], off
	s_or_b32 s98, s100, s21
	s_mov_b32 s99, 0
	s_lshl_b64 s[98:99], s[98:99], 12
	v_lshl_add_u64 v[142:143], v[126:127], 0, s[98:99]
	global_load_dwordx4 v[200:203], v[142:143], off
	s_or_b32 s98, s100, s23
	s_mov_b32 s99, 0
	s_lshl_b64 s[98:99], s[98:99], 12
	v_lshl_add_u64 v[142:143], v[126:127], 0, s[98:99]
	global_load_dwordx4 v[204:207], v[142:143], off
	ds_read_b128 v[66:69], v129
	s_lshl_b64 s[10:11], s[6:7], 11
	s_add_u32 s10, s17, s10
	s_addc_u32 s11, s18, s11
	s_add_u32 s10, s10, s4
	s_addc_u32 s11, s11, s5
	v_lshl_add_u64 v[70:71], v[130:131], 1, s[10:11]
	s_waitcnt lgkmcnt(0)
	v_pk_add_f32 v[64:65], v[64:65], v[68:69]
	v_pk_add_f32 v[62:63], v[62:63], v[66:67]
	v_cvt_pk_bf16_f32 v67, v64, v65
	v_cvt_pk_bf16_f32 v66, v62, v63
	v_mul_f32_e32 v63, v63, v63
	v_mul_f32_e32 v65, v65, v65
	v_fmac_f32_e32 v63, v62, v62
	v_fmac_f32_e32 v65, v64, v64
	v_add_f32_e32 v62, v63, v65
	global_store_dwordx2 v[70:71], v[66:67], off
	s_nop 0
	v_add_f32_dpp v62, v62, v62 quad_perm:[1,0,3,2] row_mask:0xf bank_mask:0xf bound_ctrl:1
	s_nop 1
	v_add_f32_dpp v62, v62, v62 quad_perm:[2,3,0,1] row_mask:0xf bank_mask:0xf bound_ctrl:1
	s_nop 1
	v_add_f32_dpp v62, v62, v62 row_half_mirror row_mask:0xf bank_mask:0xf bound_ctrl:1
	s_nop 1
	v_add_f32_dpp v62, v62, v62 row_mirror row_mask:0xf bank_mask:0xf bound_ctrl:1
	v_mov_b32_e32 v63, v62
	s_nop 1
	v_permlane16_swap_b32_e32 v62, v63
	v_add_f32_e32 v62, v62, v63
	v_mov_b32_e32 v63, v62
	s_nop 1
	v_permlane32_swap_b32_e32 v62, v63
	s_and_saveexec_b64 s[10:11], vcc
	s_cbranch_execz .LBB0_800
	s_lshl_b64 s[6:7], s[6:7], 4
	s_add_u32 s33, s15, s6
	s_addc_u32 s34, s16, s7
	s_lshl_b64 s[6:7], s[8:9], 2
	s_add_u32 s6, s33, s6
	s_addc_u32 s7, s34, s7
	v_mov_b32_e32 v64, 0
	v_add_f32_e32 v62, v62, v63
	global_store_dword v64, v62, s[6:7]
.LBB0_800:
	s_or_b64 exec, exec, s[10:11]
	ds_read_b128 v[62:65], v128
	s_or_b32 s6, s31, s24
	s_ashr_i32 s7, s6, 31
	s_lshl_b64 s[10:11], s[6:7], 11
	s_add_u32 s10, s17, s10
	s_waitcnt lgkmcnt(0)
	v_pk_add_f32 v[58:59], v[58:59], v[62:63]
	v_pk_add_f32 v[60:61], v[60:61], v[64:65]
	v_cvt_pk_bf16_f32 v62, v58, v59
	v_mul_f32_e32 v59, v59, v59
	v_fmac_f32_e32 v59, v58, v58
	v_mul_f32_e32 v58, v61, v61
	v_fmac_f32_e32 v58, v60, v60
	v_add_f32_e32 v58, v59, v58
	s_addc_u32 s11, s18, s11
	s_add_u32 s10, s10, s4
	v_add_f32_dpp v58, v58, v58 quad_perm:[1,0,3,2] row_mask:0xf bank_mask:0xf bound_ctrl:1
	s_addc_u32 s11, s11, s5
	v_cvt_pk_bf16_f32 v63, v60, v61
	v_add_f32_dpp v58, v58, v58 quad_perm:[2,3,0,1] row_mask:0xf bank_mask:0xf bound_ctrl:1
	v_lshl_add_u64 v[64:65], v[130:131], 1, s[10:11]
	global_store_dwordx2 v[64:65], v[62:63], off
	v_add_f32_dpp v58, v58, v58 row_half_mirror row_mask:0xf bank_mask:0xf bound_ctrl:1
	s_nop 1
	v_add_f32_dpp v58, v58, v58 row_mirror row_mask:0xf bank_mask:0xf bound_ctrl:1
	v_mov_b32_e32 v59, v58
	s_nop 1
	v_permlane16_swap_b32_e32 v58, v59
	v_add_f32_e32 v58, v58, v59
	v_mov_b32_e32 v59, v58
	s_nop 1
	v_permlane32_swap_b32_e32 v58, v59
	s_and_saveexec_b64 s[10:11], vcc
	s_cbranch_execz .LBB0_802
	s_lshl_b64 s[6:7], s[6:7], 4
	s_add_u32 s33, s15, s6
	s_addc_u32 s34, s16, s7
	s_lshl_b64 s[6:7], s[8:9], 2
	s_add_u32 s6, s33, s6
	s_addc_u32 s7, s34, s7
	v_mov_b32_e32 v60, 0
	v_add_f32_e32 v58, v58, v59
	global_store_dword v60, v58, s[6:7]
.LBB0_802:
	s_or_b64 exec, exec, s[10:11]
	ds_read_b128 v[58:61], v128 offset:1040
	s_or_b32 s6, s31, s25
	s_ashr_i32 s7, s6, 31
	s_lshl_b64 s[10:11], s[6:7], 11
	s_add_u32 s10, s17, s10
	s_waitcnt lgkmcnt(0)
	v_pk_add_f32 v[54:55], v[54:55], v[58:59]
	v_pk_add_f32 v[56:57], v[56:57], v[60:61]
	v_cvt_pk_bf16_f32 v58, v54, v55
	v_mul_f32_e32 v55, v55, v55
	v_fmac_f32_e32 v55, v54, v54
	v_mul_f32_e32 v54, v57, v57
	v_fmac_f32_e32 v54, v56, v56
	v_add_f32_e32 v54, v55, v54
	s_addc_u32 s11, s18, s11
	s_add_u32 s10, s10, s4
	v_add_f32_dpp v54, v54, v54 quad_perm:[1,0,3,2] row_mask:0xf bank_mask:0xf bound_ctrl:1
	s_addc_u32 s11, s11, s5
	v_cvt_pk_bf16_f32 v59, v56, v57
	v_add_f32_dpp v54, v54, v54 quad_perm:[2,3,0,1] row_mask:0xf bank_mask:0xf bound_ctrl:1
	v_lshl_add_u64 v[60:61], v[130:131], 1, s[10:11]
	global_store_dwordx2 v[60:61], v[58:59], off
	v_add_f32_dpp v54, v54, v54 row_half_mirror row_mask:0xf bank_mask:0xf bound_ctrl:1
	s_nop 1
	v_add_f32_dpp v54, v54, v54 row_mirror row_mask:0xf bank_mask:0xf bound_ctrl:1
	v_mov_b32_e32 v55, v54
	s_nop 1
	v_permlane16_swap_b32_e32 v54, v55
	v_add_f32_e32 v54, v54, v55
	v_mov_b32_e32 v55, v54
	s_nop 1
	v_permlane32_swap_b32_e32 v54, v55
	s_and_saveexec_b64 s[10:11], vcc
	s_cbranch_execz .LBB0_804
	s_lshl_b64 s[6:7], s[6:7], 4
	s_add_u32 s33, s15, s6
	s_addc_u32 s34, s16, s7
	s_lshl_b64 s[6:7], s[8:9], 2
	s_add_u32 s6, s33, s6
	s_addc_u32 s7, s34, s7
	v_mov_b32_e32 v56, 0
	v_add_f32_e32 v54, v54, v55
	global_store_dword v56, v54, s[6:7]
.LBB0_804:
	s_or_b64 exec, exec, s[10:11]
	ds_read_b128 v[54:57], v128 offset:2080
	s_or_b32 s6, s31, s26
	s_ashr_i32 s7, s6, 31
	s_lshl_b64 s[10:11], s[6:7], 11
	s_add_u32 s10, s17, s10
	s_waitcnt lgkmcnt(0)
	v_pk_add_f32 v[50:51], v[50:51], v[54:55]
	v_pk_add_f32 v[52:53], v[52:53], v[56:57]
	v_cvt_pk_bf16_f32 v54, v50, v51
	v_mul_f32_e32 v51, v51, v51
	v_fmac_f32_e32 v51, v50, v50
	v_mul_f32_e32 v50, v53, v53
	v_fmac_f32_e32 v50, v52, v52
	v_add_f32_e32 v50, v51, v50
	s_addc_u32 s11, s18, s11
	s_add_u32 s10, s10, s4
	v_add_f32_dpp v50, v50, v50 quad_perm:[1,0,3,2] row_mask:0xf bank_mask:0xf bound_ctrl:1
	s_addc_u32 s11, s11, s5
	v_cvt_pk_bf16_f32 v55, v52, v53
	v_add_f32_dpp v50, v50, v50 quad_perm:[2,3,0,1] row_mask:0xf bank_mask:0xf bound_ctrl:1
	v_lshl_add_u64 v[56:57], v[130:131], 1, s[10:11]
	global_store_dwordx2 v[56:57], v[54:55], off
	v_add_f32_dpp v50, v50, v50 row_half_mirror row_mask:0xf bank_mask:0xf bound_ctrl:1
	s_nop 1
	v_add_f32_dpp v50, v50, v50 row_mirror row_mask:0xf bank_mask:0xf bound_ctrl:1
	v_mov_b32_e32 v51, v50
	s_nop 1
	v_permlane16_swap_b32_e32 v50, v51
	v_add_f32_e32 v50, v50, v51
	v_mov_b32_e32 v51, v50
	s_nop 1
	v_permlane32_swap_b32_e32 v50, v51
	s_and_saveexec_b64 s[10:11], vcc
	s_cbranch_execz .LBB0_806
	s_lshl_b64 s[6:7], s[6:7], 4
	s_add_u32 s33, s15, s6
	s_addc_u32 s34, s16, s7
	s_lshl_b64 s[6:7], s[8:9], 2
	s_add_u32 s6, s33, s6
	s_addc_u32 s7, s34, s7
	v_mov_b32_e32 v52, 0
	v_add_f32_e32 v50, v50, v51
	global_store_dword v52, v50, s[6:7]
.LBB0_806:
	s_or_b64 exec, exec, s[10:11]
	ds_read_b128 v[50:53], v128 offset:3120
	s_or_b32 s6, s31, s27
	s_ashr_i32 s7, s6, 31
	s_lshl_b64 s[10:11], s[6:7], 11
	s_add_u32 s10, s17, s10
	s_waitcnt lgkmcnt(0)
	v_pk_add_f32 v[46:47], v[46:47], v[50:51]
	v_pk_add_f32 v[48:49], v[48:49], v[52:53]
	v_cvt_pk_bf16_f32 v50, v46, v47
	v_mul_f32_e32 v47, v47, v47
	v_fmac_f32_e32 v47, v46, v46
	v_mul_f32_e32 v46, v49, v49
	v_fmac_f32_e32 v46, v48, v48
	v_add_f32_e32 v46, v47, v46
	s_addc_u32 s11, s18, s11
	s_add_u32 s10, s10, s4
	v_add_f32_dpp v46, v46, v46 quad_perm:[1,0,3,2] row_mask:0xf bank_mask:0xf bound_ctrl:1
	s_addc_u32 s11, s11, s5
	v_cvt_pk_bf16_f32 v51, v48, v49
	v_add_f32_dpp v46, v46, v46 quad_perm:[2,3,0,1] row_mask:0xf bank_mask:0xf bound_ctrl:1
	v_lshl_add_u64 v[52:53], v[130:131], 1, s[10:11]
	global_store_dwordx2 v[52:53], v[50:51], off
	v_add_f32_dpp v46, v46, v46 row_half_mirror row_mask:0xf bank_mask:0xf bound_ctrl:1
	s_nop 1
	v_add_f32_dpp v46, v46, v46 row_mirror row_mask:0xf bank_mask:0xf bound_ctrl:1
	v_mov_b32_e32 v47, v46
	s_nop 1
	v_permlane16_swap_b32_e32 v46, v47
	v_add_f32_e32 v46, v46, v47
	v_mov_b32_e32 v47, v46
	s_nop 1
	v_permlane32_swap_b32_e32 v46, v47
	s_and_saveexec_b64 s[10:11], vcc
	s_cbranch_execz .LBB0_808
	s_lshl_b64 s[6:7], s[6:7], 4
	s_add_u32 s33, s15, s6
	s_addc_u32 s34, s16, s7
	s_lshl_b64 s[6:7], s[8:9], 2
	s_add_u32 s6, s33, s6
	s_addc_u32 s7, s34, s7
	v_mov_b32_e32 v48, 0
	v_add_f32_e32 v46, v46, v47
	global_store_dword v48, v46, s[6:7]
.LBB0_808:
	s_or_b64 exec, exec, s[10:11]
	ds_read_b128 v[46:49], v128 offset:4160
	s_or_b32 s6, s31, s28
	s_ashr_i32 s7, s6, 31
	s_lshl_b64 s[10:11], s[6:7], 11
	s_add_u32 s10, s17, s10
	s_waitcnt lgkmcnt(0)
	v_pk_add_f32 v[42:43], v[42:43], v[46:47]
	v_pk_add_f32 v[44:45], v[44:45], v[48:49]
	v_cvt_pk_bf16_f32 v46, v42, v43
	v_mul_f32_e32 v43, v43, v43
	v_fmac_f32_e32 v43, v42, v42
	v_mul_f32_e32 v42, v45, v45
	v_fmac_f32_e32 v42, v44, v44
	v_add_f32_e32 v42, v43, v42
	s_addc_u32 s11, s18, s11
	s_add_u32 s10, s10, s4
	v_add_f32_dpp v42, v42, v42 quad_perm:[1,0,3,2] row_mask:0xf bank_mask:0xf bound_ctrl:1
	s_addc_u32 s11, s11, s5
	v_cvt_pk_bf16_f32 v47, v44, v45
	v_add_f32_dpp v42, v42, v42 quad_perm:[2,3,0,1] row_mask:0xf bank_mask:0xf bound_ctrl:1
	v_lshl_add_u64 v[48:49], v[130:131], 1, s[10:11]
	global_store_dwordx2 v[48:49], v[46:47], off
	v_add_f32_dpp v42, v42, v42 row_half_mirror row_mask:0xf bank_mask:0xf bound_ctrl:1
	s_nop 1
	v_add_f32_dpp v42, v42, v42 row_mirror row_mask:0xf bank_mask:0xf bound_ctrl:1
	v_mov_b32_e32 v43, v42
	s_nop 1
	v_permlane16_swap_b32_e32 v42, v43
	v_add_f32_e32 v42, v42, v43
	v_mov_b32_e32 v43, v42
	s_nop 1
	v_permlane32_swap_b32_e32 v42, v43
	s_and_saveexec_b64 s[10:11], vcc
	s_cbranch_execz .LBB0_810
	s_lshl_b64 s[6:7], s[6:7], 4
	s_add_u32 s33, s15, s6
	s_addc_u32 s34, s16, s7
	s_lshl_b64 s[6:7], s[8:9], 2
	s_add_u32 s6, s33, s6
	s_addc_u32 s7, s34, s7
	v_mov_b32_e32 v44, 0
	v_add_f32_e32 v42, v42, v43
	global_store_dword v44, v42, s[6:7]
.LBB0_810:
	s_or_b64 exec, exec, s[10:11]
	ds_read_b128 v[42:45], v128 offset:5200
	s_or_b32 s6, s31, s29
	s_ashr_i32 s7, s6, 31
	s_lshl_b64 s[10:11], s[6:7], 11
	s_add_u32 s10, s17, s10
	s_waitcnt lgkmcnt(0)
	v_pk_add_f32 v[38:39], v[38:39], v[42:43]
	v_pk_add_f32 v[40:41], v[40:41], v[44:45]
	v_cvt_pk_bf16_f32 v42, v38, v39
	v_mul_f32_e32 v39, v39, v39
	v_fmac_f32_e32 v39, v38, v38
	v_mul_f32_e32 v38, v41, v41
	v_fmac_f32_e32 v38, v40, v40
	v_add_f32_e32 v38, v39, v38
	s_addc_u32 s11, s18, s11
	s_add_u32 s10, s10, s4
	v_add_f32_dpp v38, v38, v38 quad_perm:[1,0,3,2] row_mask:0xf bank_mask:0xf bound_ctrl:1
	s_addc_u32 s11, s11, s5
	v_cvt_pk_bf16_f32 v43, v40, v41
	v_add_f32_dpp v38, v38, v38 quad_perm:[2,3,0,1] row_mask:0xf bank_mask:0xf bound_ctrl:1
	v_lshl_add_u64 v[44:45], v[130:131], 1, s[10:11]
	global_store_dwordx2 v[44:45], v[42:43], off
	v_add_f32_dpp v38, v38, v38 row_half_mirror row_mask:0xf bank_mask:0xf bound_ctrl:1
	s_nop 1
	v_add_f32_dpp v38, v38, v38 row_mirror row_mask:0xf bank_mask:0xf bound_ctrl:1
	v_mov_b32_e32 v39, v38
	s_nop 1
	v_permlane16_swap_b32_e32 v38, v39
	v_add_f32_e32 v38, v38, v39
	v_mov_b32_e32 v39, v38
	s_nop 1
	v_permlane32_swap_b32_e32 v38, v39
	s_and_saveexec_b64 s[10:11], vcc
	s_cbranch_execz .LBB0_812
	s_lshl_b64 s[6:7], s[6:7], 4
	s_add_u32 s33, s15, s6
	s_addc_u32 s34, s16, s7
	s_lshl_b64 s[6:7], s[8:9], 2
	s_add_u32 s6, s33, s6
	s_addc_u32 s7, s34, s7
	v_mov_b32_e32 v40, 0
	v_add_f32_e32 v38, v38, v39
	global_store_dword v40, v38, s[6:7]
.LBB0_812:
	s_or_b64 exec, exec, s[10:11]
	ds_read_b128 v[38:41], v128 offset:6240
	s_or_b32 s6, s31, s30
	s_ashr_i32 s7, s6, 31
	s_lshl_b64 s[10:11], s[6:7], 11
	s_add_u32 s10, s17, s10
	s_waitcnt lgkmcnt(0)
	v_pk_add_f32 v[34:35], v[34:35], v[38:39]
	v_pk_add_f32 v[36:37], v[36:37], v[40:41]
	v_cvt_pk_bf16_f32 v38, v34, v35
	v_mul_f32_e32 v35, v35, v35
	v_fmac_f32_e32 v35, v34, v34
	v_mul_f32_e32 v34, v37, v37
	v_fmac_f32_e32 v34, v36, v36
	v_add_f32_e32 v34, v35, v34
	s_addc_u32 s11, s18, s11
	s_add_u32 s10, s10, s4
	v_add_f32_dpp v34, v34, v34 quad_perm:[1,0,3,2] row_mask:0xf bank_mask:0xf bound_ctrl:1
	s_addc_u32 s11, s11, s5
	v_cvt_pk_bf16_f32 v39, v36, v37
	v_add_f32_dpp v34, v34, v34 quad_perm:[2,3,0,1] row_mask:0xf bank_mask:0xf bound_ctrl:1
	v_lshl_add_u64 v[40:41], v[130:131], 1, s[10:11]
	global_store_dwordx2 v[40:41], v[38:39], off
	v_add_f32_dpp v34, v34, v34 row_half_mirror row_mask:0xf bank_mask:0xf bound_ctrl:1
	s_nop 1
	v_add_f32_dpp v34, v34, v34 row_mirror row_mask:0xf bank_mask:0xf bound_ctrl:1
	v_mov_b32_e32 v35, v34
	s_nop 1
	v_permlane16_swap_b32_e32 v34, v35
	v_add_f32_e32 v34, v34, v35
	v_mov_b32_e32 v35, v34
	s_nop 1
	v_permlane32_swap_b32_e32 v34, v35
	s_and_saveexec_b64 s[10:11], vcc
	s_cbranch_execz .LBB0_814
	s_lshl_b64 s[6:7], s[6:7], 4
	s_add_u32 s33, s15, s6
	s_addc_u32 s34, s16, s7
	s_lshl_b64 s[6:7], s[8:9], 2
	s_add_u32 s6, s33, s6
	s_addc_u32 s7, s34, s7
	v_mov_b32_e32 v36, 0
	v_add_f32_e32 v34, v34, v35
	global_store_dword v36, v34, s[6:7]
.LBB0_814:
	s_or_b64 exec, exec, s[10:11]
	s_or_b32 s31, s31, 32
	s_or_b32 s6, s31, s19
	s_ashr_i32 s7, s6, 31
	s_lshl_b64 s[10:11], s[6:7], 12
	s_barrier
	ds_write_b128 v132, v[30:33]
	ds_write_b128 v132, v[26:29] offset:16
	ds_write_b128 v132, v[14:17] offset:512
	ds_write_b128 v132, v[10:13] offset:528
	ds_write_b128 v132, v[22:25] offset:16640
	ds_write_b128 v132, v[18:21] offset:16656
	ds_write_b128 v132, v[6:9] offset:17152
	ds_write_b128 v132, v[2:5] offset:17168
	v_lshl_add_u64 v[2:3], v[126:127], 0, s[10:11]
	s_or_b32 s10, s31, s12
	s_ashr_i32 s11, s10, 31
	s_lshl_b64 s[10:11], s[10:11], 12
	v_lshl_add_u64 v[4:5], v[126:127], 0, s[10:11]
	s_or_b32 s10, s31, s13
	s_ashr_i32 s11, s10, 31
	s_lshl_b64 s[10:11], s[10:11], 12
	s_waitcnt lgkmcnt(0)
	s_barrier
	s_waitcnt vmcnt(8)
	v_mov_b32_e32 v30, v176
	v_mov_b32_e32 v31, v177
	v_mov_b32_e32 v32, v178
	v_mov_b32_e32 v33, v179
	v_mov_b32_e32 v26, v180
	v_mov_b32_e32 v27, v181
	v_mov_b32_e32 v28, v182
	v_mov_b32_e32 v29, v183
	v_mov_b32_e32 v22, v184
	v_mov_b32_e32 v23, v185
	v_mov_b32_e32 v24, v186
	v_mov_b32_e32 v25, v187
	v_mov_b32_e32 v18, v188
	v_mov_b32_e32 v19, v189
	v_mov_b32_e32 v20, v190
	v_mov_b32_e32 v21, v191
	v_mov_b32_e32 v14, v192
	v_mov_b32_e32 v15, v193
	v_mov_b32_e32 v16, v194
	v_mov_b32_e32 v17, v195
	v_mov_b32_e32 v10, v196
	v_mov_b32_e32 v11, v197
	v_mov_b32_e32 v12, v198
	v_mov_b32_e32 v13, v199
	v_mov_b32_e32 v6, v200
	v_mov_b32_e32 v7, v201
	v_mov_b32_e32 v8, v202
	v_mov_b32_e32 v9, v203
	v_mov_b32_e32 v2, v204
	v_mov_b32_e32 v3, v205
	v_mov_b32_e32 v4, v206
	v_mov_b32_e32 v5, v207
	ds_read_b128 v[34:37], v129
	s_lshl_b64 s[10:11], s[6:7], 11
	s_add_u32 s10, s17, s10
	s_addc_u32 s11, s18, s11
	s_add_u32 s10, s10, s4
	s_addc_u32 s11, s11, s5
	v_lshl_add_u64 v[38:39], v[130:131], 1, s[10:11]
	s_waitcnt lgkmcnt(0)
	v_pk_add_f32 v[32:33], v[32:33], v[36:37]
	v_pk_add_f32 v[30:31], v[30:31], v[34:35]
	v_cvt_pk_bf16_f32 v35, v32, v33
	v_cvt_pk_bf16_f32 v34, v30, v31
	v_mul_f32_e32 v31, v31, v31
	v_mul_f32_e32 v33, v33, v33
	v_fmac_f32_e32 v31, v30, v30
	v_fmac_f32_e32 v33, v32, v32
	v_add_f32_e32 v30, v31, v33
	global_store_dwordx2 v[38:39], v[34:35], off
	s_nop 0
	v_add_f32_dpp v30, v30, v30 quad_perm:[1,0,3,2] row_mask:0xf bank_mask:0xf bound_ctrl:1
	s_nop 1
	v_add_f32_dpp v30, v30, v30 quad_perm:[2,3,0,1] row_mask:0xf bank_mask:0xf bound_ctrl:1
	s_nop 1
	v_add_f32_dpp v30, v30, v30 row_half_mirror row_mask:0xf bank_mask:0xf bound_ctrl:1
	s_nop 1
	v_add_f32_dpp v30, v30, v30 row_mirror row_mask:0xf bank_mask:0xf bound_ctrl:1
	v_mov_b32_e32 v31, v30
	s_nop 1
	v_permlane16_swap_b32_e32 v30, v31
	v_add_f32_e32 v30, v30, v31
	v_mov_b32_e32 v31, v30
	s_nop 1
	v_permlane32_swap_b32_e32 v30, v31
	s_and_saveexec_b64 s[10:11], vcc
	s_cbranch_execz .LBB0_816
	s_lshl_b64 s[6:7], s[6:7], 4
	s_add_u32 s12, s15, s6
	s_addc_u32 s13, s16, s7
	s_lshl_b64 s[6:7], s[8:9], 2
	s_add_u32 s6, s12, s6
	s_addc_u32 s7, s13, s7
	v_mov_b32_e32 v32, 0
	v_add_f32_e32 v30, v30, v31
	global_store_dword v32, v30, s[6:7]
.LBB0_816:
	s_or_b64 exec, exec, s[10:11]
	ds_read_b128 v[30:33], v128
	s_or_b32 s6, s31, s24
	s_ashr_i32 s7, s6, 31
	s_lshl_b64 s[10:11], s[6:7], 11
	s_add_u32 s10, s17, s10
	s_waitcnt lgkmcnt(0)
	v_pk_add_f32 v[26:27], v[26:27], v[30:31]
	v_pk_add_f32 v[28:29], v[28:29], v[32:33]
	v_cvt_pk_bf16_f32 v30, v26, v27
	v_mul_f32_e32 v27, v27, v27
	v_fmac_f32_e32 v27, v26, v26
	v_mul_f32_e32 v26, v29, v29
	v_fmac_f32_e32 v26, v28, v28
	v_add_f32_e32 v26, v27, v26
	s_addc_u32 s11, s18, s11
	s_add_u32 s10, s10, s4
	v_add_f32_dpp v26, v26, v26 quad_perm:[1,0,3,2] row_mask:0xf bank_mask:0xf bound_ctrl:1
	s_addc_u32 s11, s11, s5
	v_cvt_pk_bf16_f32 v31, v28, v29
	v_add_f32_dpp v26, v26, v26 quad_perm:[2,3,0,1] row_mask:0xf bank_mask:0xf bound_ctrl:1
	v_lshl_add_u64 v[32:33], v[130:131], 1, s[10:11]
	global_store_dwordx2 v[32:33], v[30:31], off
	v_add_f32_dpp v26, v26, v26 row_half_mirror row_mask:0xf bank_mask:0xf bound_ctrl:1
	s_nop 1
	v_add_f32_dpp v26, v26, v26 row_mirror row_mask:0xf bank_mask:0xf bound_ctrl:1
	v_mov_b32_e32 v27, v26
	s_nop 1
	v_permlane16_swap_b32_e32 v26, v27
	v_add_f32_e32 v26, v26, v27
	v_mov_b32_e32 v27, v26
	s_nop 1
	v_permlane32_swap_b32_e32 v26, v27
	s_and_saveexec_b64 s[10:11], vcc
	s_cbranch_execz .LBB0_818
	s_lshl_b64 s[6:7], s[6:7], 4
	s_add_u32 s12, s15, s6
	s_addc_u32 s13, s16, s7
	s_lshl_b64 s[6:7], s[8:9], 2
	s_add_u32 s6, s12, s6
	s_addc_u32 s7, s13, s7
	v_mov_b32_e32 v28, 0
	v_add_f32_e32 v26, v26, v27
	global_store_dword v28, v26, s[6:7]
.LBB0_818:
	s_or_b64 exec, exec, s[10:11]
	ds_read_b128 v[26:29], v128 offset:1040
	s_or_b32 s6, s31, s25
	s_ashr_i32 s7, s6, 31
	s_lshl_b64 s[10:11], s[6:7], 11
	s_add_u32 s10, s17, s10
	s_waitcnt lgkmcnt(0)
	v_pk_add_f32 v[22:23], v[22:23], v[26:27]
	v_pk_add_f32 v[24:25], v[24:25], v[28:29]
	v_cvt_pk_bf16_f32 v26, v22, v23
	v_mul_f32_e32 v23, v23, v23
	v_fmac_f32_e32 v23, v22, v22
	v_mul_f32_e32 v22, v25, v25
	v_fmac_f32_e32 v22, v24, v24
	v_add_f32_e32 v22, v23, v22
	s_addc_u32 s11, s18, s11
	s_add_u32 s10, s10, s4
	v_add_f32_dpp v22, v22, v22 quad_perm:[1,0,3,2] row_mask:0xf bank_mask:0xf bound_ctrl:1
	s_addc_u32 s11, s11, s5
	v_cvt_pk_bf16_f32 v27, v24, v25
	v_add_f32_dpp v22, v22, v22 quad_perm:[2,3,0,1] row_mask:0xf bank_mask:0xf bound_ctrl:1
	v_lshl_add_u64 v[28:29], v[130:131], 1, s[10:11]
	global_store_dwordx2 v[28:29], v[26:27], off
	v_add_f32_dpp v22, v22, v22 row_half_mirror row_mask:0xf bank_mask:0xf bound_ctrl:1
	s_nop 1
	v_add_f32_dpp v22, v22, v22 row_mirror row_mask:0xf bank_mask:0xf bound_ctrl:1
	v_mov_b32_e32 v23, v22
	s_nop 1
	v_permlane16_swap_b32_e32 v22, v23
	v_add_f32_e32 v22, v22, v23
	v_mov_b32_e32 v23, v22
	s_nop 1
	v_permlane32_swap_b32_e32 v22, v23
	s_and_saveexec_b64 s[10:11], vcc
	s_cbranch_execz .LBB0_820
	s_lshl_b64 s[6:7], s[6:7], 4
	s_add_u32 s12, s15, s6
	s_addc_u32 s13, s16, s7
	s_lshl_b64 s[6:7], s[8:9], 2
	s_add_u32 s6, s12, s6
	s_addc_u32 s7, s13, s7
	v_mov_b32_e32 v24, 0
	v_add_f32_e32 v22, v22, v23
	global_store_dword v24, v22, s[6:7]
.LBB0_820:
	s_or_b64 exec, exec, s[10:11]
	ds_read_b128 v[22:25], v128 offset:2080
	s_or_b32 s6, s31, s26
	s_ashr_i32 s7, s6, 31
	s_lshl_b64 s[10:11], s[6:7], 11
	s_add_u32 s10, s17, s10
	s_waitcnt lgkmcnt(0)
	v_pk_add_f32 v[18:19], v[18:19], v[22:23]
	v_pk_add_f32 v[20:21], v[20:21], v[24:25]
	v_cvt_pk_bf16_f32 v22, v18, v19
	v_mul_f32_e32 v19, v19, v19
	v_fmac_f32_e32 v19, v18, v18
	v_mul_f32_e32 v18, v21, v21
	v_fmac_f32_e32 v18, v20, v20
	v_add_f32_e32 v18, v19, v18
	s_addc_u32 s11, s18, s11
	s_add_u32 s10, s10, s4
	v_add_f32_dpp v18, v18, v18 quad_perm:[1,0,3,2] row_mask:0xf bank_mask:0xf bound_ctrl:1
	s_addc_u32 s11, s11, s5
	v_cvt_pk_bf16_f32 v23, v20, v21
	v_add_f32_dpp v18, v18, v18 quad_perm:[2,3,0,1] row_mask:0xf bank_mask:0xf bound_ctrl:1
	v_lshl_add_u64 v[24:25], v[130:131], 1, s[10:11]
	global_store_dwordx2 v[24:25], v[22:23], off
	v_add_f32_dpp v18, v18, v18 row_half_mirror row_mask:0xf bank_mask:0xf bound_ctrl:1
	s_nop 1
	v_add_f32_dpp v18, v18, v18 row_mirror row_mask:0xf bank_mask:0xf bound_ctrl:1
	v_mov_b32_e32 v19, v18
	s_nop 1
	v_permlane16_swap_b32_e32 v18, v19
	v_add_f32_e32 v18, v18, v19
	v_mov_b32_e32 v19, v18
	s_nop 1
	v_permlane32_swap_b32_e32 v18, v19
	s_and_saveexec_b64 s[10:11], vcc
	s_cbranch_execz .LBB0_822
	s_lshl_b64 s[6:7], s[6:7], 4
	s_add_u32 s12, s15, s6
	s_addc_u32 s13, s16, s7
	s_lshl_b64 s[6:7], s[8:9], 2
	s_add_u32 s6, s12, s6
	s_addc_u32 s7, s13, s7
	v_mov_b32_e32 v20, 0
	v_add_f32_e32 v18, v18, v19
	global_store_dword v20, v18, s[6:7]
.LBB0_822:
	s_or_b64 exec, exec, s[10:11]
	ds_read_b128 v[18:21], v128 offset:3120
	s_or_b32 s6, s31, s27
	s_ashr_i32 s7, s6, 31
	s_lshl_b64 s[10:11], s[6:7], 11
	s_add_u32 s10, s17, s10
	s_waitcnt lgkmcnt(0)
	v_pk_add_f32 v[14:15], v[14:15], v[18:19]
	v_pk_add_f32 v[16:17], v[16:17], v[20:21]
	v_cvt_pk_bf16_f32 v18, v14, v15
	v_mul_f32_e32 v15, v15, v15
	v_fmac_f32_e32 v15, v14, v14
	v_mul_f32_e32 v14, v17, v17
	v_fmac_f32_e32 v14, v16, v16
	v_add_f32_e32 v14, v15, v14
	s_addc_u32 s11, s18, s11
	s_add_u32 s10, s10, s4
	v_add_f32_dpp v14, v14, v14 quad_perm:[1,0,3,2] row_mask:0xf bank_mask:0xf bound_ctrl:1
	s_addc_u32 s11, s11, s5
	v_cvt_pk_bf16_f32 v19, v16, v17
	v_add_f32_dpp v14, v14, v14 quad_perm:[2,3,0,1] row_mask:0xf bank_mask:0xf bound_ctrl:1
	v_lshl_add_u64 v[20:21], v[130:131], 1, s[10:11]
	global_store_dwordx2 v[20:21], v[18:19], off
	v_add_f32_dpp v14, v14, v14 row_half_mirror row_mask:0xf bank_mask:0xf bound_ctrl:1
	s_nop 1
	v_add_f32_dpp v14, v14, v14 row_mirror row_mask:0xf bank_mask:0xf bound_ctrl:1
	v_mov_b32_e32 v15, v14
	s_nop 1
	v_permlane16_swap_b32_e32 v14, v15
	v_add_f32_e32 v14, v14, v15
	v_mov_b32_e32 v15, v14
	s_nop 1
	v_permlane32_swap_b32_e32 v14, v15
	s_and_saveexec_b64 s[10:11], vcc
	s_cbranch_execz .LBB0_824
	s_lshl_b64 s[6:7], s[6:7], 4
	s_add_u32 s12, s15, s6
	s_addc_u32 s13, s16, s7
	s_lshl_b64 s[6:7], s[8:9], 2
	s_add_u32 s6, s12, s6
	s_addc_u32 s7, s13, s7
	v_mov_b32_e32 v16, 0
	v_add_f32_e32 v14, v14, v15
	global_store_dword v16, v14, s[6:7]
.LBB0_824:
	s_or_b64 exec, exec, s[10:11]
	ds_read_b128 v[14:17], v128 offset:4160
	s_or_b32 s6, s31, s28
	s_ashr_i32 s7, s6, 31
	s_lshl_b64 s[10:11], s[6:7], 11
	s_add_u32 s10, s17, s10
	s_waitcnt lgkmcnt(0)
	v_pk_add_f32 v[10:11], v[10:11], v[14:15]
	v_pk_add_f32 v[12:13], v[12:13], v[16:17]
	v_cvt_pk_bf16_f32 v14, v10, v11
	v_mul_f32_e32 v11, v11, v11
	v_fmac_f32_e32 v11, v10, v10
	v_mul_f32_e32 v10, v13, v13
	v_fmac_f32_e32 v10, v12, v12
	v_add_f32_e32 v10, v11, v10
	s_addc_u32 s11, s18, s11
	s_add_u32 s10, s10, s4
	v_add_f32_dpp v10, v10, v10 quad_perm:[1,0,3,2] row_mask:0xf bank_mask:0xf bound_ctrl:1
	s_addc_u32 s11, s11, s5
	v_cvt_pk_bf16_f32 v15, v12, v13
	v_add_f32_dpp v10, v10, v10 quad_perm:[2,3,0,1] row_mask:0xf bank_mask:0xf bound_ctrl:1
	v_lshl_add_u64 v[16:17], v[130:131], 1, s[10:11]
	global_store_dwordx2 v[16:17], v[14:15], off
	v_add_f32_dpp v10, v10, v10 row_half_mirror row_mask:0xf bank_mask:0xf bound_ctrl:1
	s_nop 1
	v_add_f32_dpp v10, v10, v10 row_mirror row_mask:0xf bank_mask:0xf bound_ctrl:1
	v_mov_b32_e32 v11, v10
	s_nop 1
	v_permlane16_swap_b32_e32 v10, v11
	v_add_f32_e32 v10, v10, v11
	v_mov_b32_e32 v11, v10
	s_nop 1
	v_permlane32_swap_b32_e32 v10, v11
	s_and_saveexec_b64 s[10:11], vcc
	s_cbranch_execz .LBB0_826
	s_lshl_b64 s[6:7], s[6:7], 4
	s_add_u32 s12, s15, s6
	s_addc_u32 s13, s16, s7
	s_lshl_b64 s[6:7], s[8:9], 2
	s_add_u32 s6, s12, s6
	s_addc_u32 s7, s13, s7
	v_mov_b32_e32 v12, 0
	v_add_f32_e32 v10, v10, v11
	global_store_dword v12, v10, s[6:7]
.LBB0_826:
	s_or_b64 exec, exec, s[10:11]
	ds_read_b128 v[10:13], v128 offset:5200
	s_or_b32 s6, s31, s29
	s_ashr_i32 s7, s6, 31
	s_lshl_b64 s[10:11], s[6:7], 11
	s_add_u32 s10, s17, s10
	s_waitcnt lgkmcnt(0)
	v_pk_add_f32 v[6:7], v[6:7], v[10:11]
	v_pk_add_f32 v[8:9], v[8:9], v[12:13]
	v_cvt_pk_bf16_f32 v10, v6, v7
	v_mul_f32_e32 v7, v7, v7
	v_fmac_f32_e32 v7, v6, v6
	v_mul_f32_e32 v6, v9, v9
	v_fmac_f32_e32 v6, v8, v8
	v_add_f32_e32 v6, v7, v6
	s_addc_u32 s11, s18, s11
	s_add_u32 s10, s10, s4
	v_add_f32_dpp v6, v6, v6 quad_perm:[1,0,3,2] row_mask:0xf bank_mask:0xf bound_ctrl:1
	s_addc_u32 s11, s11, s5
	v_cvt_pk_bf16_f32 v11, v8, v9
	v_add_f32_dpp v6, v6, v6 quad_perm:[2,3,0,1] row_mask:0xf bank_mask:0xf bound_ctrl:1
	v_lshl_add_u64 v[12:13], v[130:131], 1, s[10:11]
	global_store_dwordx2 v[12:13], v[10:11], off
	v_add_f32_dpp v6, v6, v6 row_half_mirror row_mask:0xf bank_mask:0xf bound_ctrl:1
	s_nop 1
	v_add_f32_dpp v6, v6, v6 row_mirror row_mask:0xf bank_mask:0xf bound_ctrl:1
	v_mov_b32_e32 v7, v6
	s_nop 1
	v_permlane16_swap_b32_e32 v6, v7
	v_add_f32_e32 v6, v6, v7
	v_mov_b32_e32 v7, v6
	s_nop 1
	v_permlane32_swap_b32_e32 v6, v7
	s_and_saveexec_b64 s[10:11], vcc
	s_cbranch_execz .LBB0_828
	s_lshl_b64 s[6:7], s[6:7], 4
	s_add_u32 s12, s15, s6
	s_addc_u32 s13, s16, s7
	s_lshl_b64 s[6:7], s[8:9], 2
	s_add_u32 s6, s12, s6
	s_addc_u32 s7, s13, s7
	v_mov_b32_e32 v8, 0
	v_add_f32_e32 v6, v6, v7
	global_store_dword v8, v6, s[6:7]
.LBB0_828:
	s_or_b64 exec, exec, s[10:11]
	ds_read_b128 v[6:9], v128 offset:6240
	s_or_b32 s6, s31, s30
	s_ashr_i32 s7, s6, 31
	s_lshl_b64 s[10:11], s[6:7], 11
	s_add_u32 s10, s17, s10
	s_waitcnt lgkmcnt(0)
	v_pk_add_f32 v[2:3], v[2:3], v[6:7]
	v_pk_add_f32 v[4:5], v[4:5], v[8:9]
	v_cvt_pk_bf16_f32 v6, v2, v3
	v_mul_f32_e32 v3, v3, v3
	v_fmac_f32_e32 v3, v2, v2
	v_mul_f32_e32 v2, v5, v5
	v_fmac_f32_e32 v2, v4, v4
	v_add_f32_e32 v2, v3, v2
	s_addc_u32 s11, s18, s11
	s_add_u32 s4, s10, s4
	v_add_f32_dpp v2, v2, v2 quad_perm:[1,0,3,2] row_mask:0xf bank_mask:0xf bound_ctrl:1
	s_addc_u32 s5, s11, s5
	v_cvt_pk_bf16_f32 v7, v4, v5
	v_add_f32_dpp v2, v2, v2 quad_perm:[2,3,0,1] row_mask:0xf bank_mask:0xf bound_ctrl:1
	v_lshl_add_u64 v[8:9], v[130:131], 1, s[4:5]
	global_store_dwordx2 v[8:9], v[6:7], off
	v_add_f32_dpp v2, v2, v2 row_half_mirror row_mask:0xf bank_mask:0xf bound_ctrl:1
	s_nop 1
	v_add_f32_dpp v2, v2, v2 row_mirror row_mask:0xf bank_mask:0xf bound_ctrl:1
	v_mov_b32_e32 v3, v2
	s_nop 1
	v_permlane16_swap_b32_e32 v2, v3
	v_add_f32_e32 v2, v2, v3
	v_mov_b32_e32 v3, v2
	s_nop 1
	v_permlane32_swap_b32_e32 v2, v3
	s_and_saveexec_b64 s[4:5], vcc
	s_cbranch_execz .LBB0_830
	s_lshl_b64 s[6:7], s[6:7], 4
	s_add_u32 s10, s15, s6
	s_addc_u32 s11, s16, s7
	s_lshl_b64 s[6:7], s[8:9], 2
	s_add_u32 s6, s10, s6
	s_addc_u32 s7, s11, s7
	v_mov_b32_e32 v4, 0
	v_add_f32_e32 v2, v2, v3
	global_store_dword v4, v2, s[6:7]
